# conv phase: per 64x64 tile the 2-3 xbc slice loads and conv tap/bias loads issued together before any wait (was 3-4 serial load->wait round trips per tile); on top of v29
# baseline (speedup 1.0000x reference)
; __device__ __forceinline__ void conv_phase(CParams& p, int layer, float* smf) {
;     ...
;         lds_sync();
;         for (int e = tid; e < 66 * 8; e += 256) {
;             const int rr = e >> 3, c8 = (e & 7) * 8;
;             const int row = r0 - 1 + rr;
;             u32x4 v = (u32x4){0u, 0u, 0u, 0u};
;             if (!((rr == 0 && first) || (rr == 65 && last))) v = *(const u32x4*)(xbc + (size_t)row * 3072 + c0 + c8);
;             float* d = sin_ + rr * 65 + c8;
;             d[0] = __uint_as_float(v.x << 16); d[1] = __uint_as_float(v.x & 0xffff0000u);
;             d[2] = __uint_as_float(v.y << 16); d[3] = __uint_as_float(v.y & 0xffff0000u);
;             d[4] = __uint_as_float(v.z << 16); d[5] = __uint_as_float(v.z & 0xffff0000u);
;             d[6] = __uint_as_float(v.w << 16); d[7] = __uint_as_float(v.w & 0xffff0000u);
;         }
;         lds_sync();
;         {
;             const int c = tid & 63;
;             const float w0 = cw[c0 + c], w1 = cw[3072 + c0 + c], w2 = cw[2 * 3072 + c0 + c], bb = cb[c0 + c];
.LBB0_406:
	s_mul_hi_i32 s14, s48, 0x2aaaaaab
	s_lshr_b32 s15, s14, 31
	s_ashr_i32 s17, s14, 3
	s_add_i32 s17, s17, s15
	s_mul_i32 s15, s17, 0xffffffd0
	s_add_i32 s15, s15, s48
	s_lshl_b32 s14, s17, 6
	s_lshl_b32 s16, s15, 6
	s_waitcnt vmcnt(63) expcnt(7) lgkmcnt(15)
	s_barrier
	s_and_saveexec_b64 s[18:19], s[42:43]
	s_cbranch_execz .LBB0_411
	s_cmpk_lt_i32 s48, 0x3000
	s_cselect_b32 s20, 0x7f, 3
	s_movk_i32 s21, 0x1fc0
	s_cselect_b32 s22, s21, 0xc0
	s_and_b32 s17, s20, s17
	s_cmp_eq_u32 s17, 0
	s_cselect_b64 s[20:21], -1, 0
	s_add_i32 s17, s14, 64
	s_and_b32 s17, s17, s22
	s_cmp_eq_u32 s17, 0
	s_cselect_b64 s[22:23], -1, 0
	s_ashr_i32 s17, s16, 31
	s_add_i32 s49, s14, -1
	s_lshl_b64 s[24:25], s[16:17], 1
	s_add_u32 s24, s46, s24
	s_addc_u32 s25, s47, s25
	s_mov_b64 s[26:27], exec
	v_and_b32_e32 v7, 56, v42
	v_ashrrev_i32_e32 v6, 3, v9
	v_lshlrev_b32_e32 v164, 1, v7
	v_add_u32_e32 v2, s49, v6
	v_mov_b64_e32 v[0:1], s[24:25]
	s_movk_i32 s2, 0x1800
	v_mad_i64_i32 v[0:1], s[50:51], v2, s2, v[0:1]
	v_lshl_add_u64 v[0:1], v[0:1], 0, v[164:165]
	v_mov_b32_e32 v48, 0
	v_mov_b32_e32 v49, 0
	v_mov_b32_e32 v50, 0
	v_mov_b32_e32 v51, 0
	v_mov_b32_e32 v56, 0
	v_mov_b32_e32 v57, 0
	v_mov_b32_e32 v58, 0
	v_mov_b32_e32 v59, 0
	s_mov_b64 s[44:45], 0x60000
	v_lshl_add_u64 v[2:3], v[0:1], 0, s[44:45]
	v_cmp_gt_u32_e64 s[44:45], 8, v9
	v_cmp_gt_u32_e32 vcc, 16, v9
	s_nop 1
	s_andn2_b64 s[50:51], vcc, s[22:23]
	s_or_b64 s[44:45], s[44:45], s[50:51]
	s_and_b64 exec, s[26:27], s[44:45]
	global_load_dwordx4 v[56:59], v[2:3], off
	s_mov_b64 exec, s[26:27]
	v_cmp_gt_u32_e32 vcc, 8, v9
	s_nop 1
	s_and_b64 s[44:45], s[20:21], vcc
	s_andn2_b64 exec, s[26:27], s[44:45]
	global_load_dwordx4 v[48:51], v[0:1], off
	s_mov_b64 exec, s[26:27]
	s_mov_b64 s[44:45], 0x30000
	v_lshl_add_u64 v[2:3], v[0:1], 0, s[44:45]
	global_load_dwordx4 v[52:55], v[2:3], off
	v_or_b32_e32 v60, s16, v16
	v_ashrrev_i32_e32 v61, 31, v60
	v_add_u32_e32 v62, s16, v17
	v_lshlrev_b64 v[64:65], 2, v[60:61]
	v_ashrrev_i32_e32 v63, 31, v62
	v_lshl_add_u64 v[60:61], s[8:9], 0, v[64:65]
	v_lshl_add_u64 v[62:63], v[62:63], 2, s[8:9]
	global_load_dword v66, v[60:61], off
	v_lshl_add_u64 v[64:65], s[12:13], 0, v[64:65]
	global_load_dword v67, v[62:63], off
	v_add_u32_e32 v62, s16, v18
	v_ashrrev_i32_e32 v63, 31, v62
	v_lshl_add_u64 v[62:63], v[62:63], 2, s[8:9]
	global_load_dword v68, v[62:63], off
	global_load_dword v69, v[64:65], off
	v_mul_lo_u32 v70, v6, s94
	v_lshlrev_b32_e32 v71, 2, v7
	v_add3_u32 v70, 0, v70, v71
	v_add_u32_e32 v71, 0x2080, v70
	v_add_u32_e32 v72, 0x4100, v70
	s_waitcnt vmcnt(5)
	v_lshlrev_b32_e32 v73, 16, v48
	v_and_b32_e32 v74, 0xffff0000, v48
	ds_write2_b32 v70, v73, v74 offset1:1
	v_lshlrev_b32_e32 v75, 16, v49
	v_and_b32_e32 v76, 0xffff0000, v49
	ds_write2_b32 v70, v75, v76 offset0:2 offset1:3
	v_lshlrev_b32_e32 v73, 16, v50
	v_and_b32_e32 v74, 0xffff0000, v50
	ds_write2_b32 v70, v73, v74 offset0:4 offset1:5
	v_lshlrev_b32_e32 v75, 16, v51
	v_and_b32_e32 v76, 0xffff0000, v51
	ds_write2_b32 v70, v75, v76 offset0:6 offset1:7
	s_waitcnt vmcnt(4)
	v_lshlrev_b32_e32 v73, 16, v52
	v_and_b32_e32 v74, 0xffff0000, v52
	ds_write2_b32 v71, v73, v74 offset1:1
	v_lshlrev_b32_e32 v75, 16, v53
	v_and_b32_e32 v76, 0xffff0000, v53
	ds_write2_b32 v71, v75, v76 offset0:2 offset1:3
	v_lshlrev_b32_e32 v73, 16, v54
	v_and_b32_e32 v74, 0xffff0000, v54
	ds_write2_b32 v71, v73, v74 offset0:4 offset1:5
	v_lshlrev_b32_e32 v75, 16, v55
	v_and_b32_e32 v76, 0xffff0000, v55
	ds_write2_b32 v71, v75, v76 offset0:6 offset1:7
	v_cmp_gt_u32_e32 vcc, 16, v9
	s_nop 1
	s_and_b64 exec, s[26:27], vcc
	v_lshlrev_b32_e32 v73, 16, v56
	v_and_b32_e32 v74, 0xffff0000, v56
	ds_write2_b32 v72, v73, v74 offset1:1
	v_lshlrev_b32_e32 v75, 16, v57
	v_and_b32_e32 v76, 0xffff0000, v57
	ds_write2_b32 v72, v75, v76 offset0:2 offset1:3
	v_lshlrev_b32_e32 v73, 16, v58
	v_and_b32_e32 v74, 0xffff0000, v58
	ds_write2_b32 v72, v73, v74 offset0:4 offset1:5
	v_lshlrev_b32_e32 v75, 16, v59
	v_and_b32_e32 v76, 0xffff0000, v59
	ds_write2_b32 v72, v75, v76 offset0:6 offset1:7
	s_mov_b64 exec, s[26:27]
.LBB0_411:
	s_or_b64 exec, exec, s[18:19]
	v_or_b32_e32 v0, s16, v16
	v_ashrrev_i32_e32 v1, 31, v0
	v_add_u32_e32 v2, s16, v17
	v_lshlrev_b64 v[4:5], 2, v[0:1]
	v_ashrrev_i32_e32 v3, 31, v2
	v_lshl_add_u64 v[0:1], s[8:9], 0, v[4:5]
	v_lshl_add_u64 v[2:3], v[2:3], 2, s[8:9]
	s_waitcnt lgkmcnt(0)
	s_barrier
; __device__ __forceinline__ float siluf(float v) { return v / (1.f + __expf(-v)); }
; __device__ __forceinline__ void conv_phase(CParams& p, int layer, float* smf) {
;     ...
;         {
;             const int c = tid & 63;
;             const float w0 = cw[c0 + c], w1 = cw[3072 + c0 + c], w2 = cw[2 * 3072 + c0 + c], bb = cb[c0 + c];
; #pragma unroll
;             for (int k = 0; k < 16; ++k) {
;                 const int tt = (tid >> 6) + k * 4;
;                 const float v = w0 * sin_[tt * 65 + c] + w1 * sin_[(tt + 1) * 65 + c] + w2 * sin_[(tt + 2) * 65 + c] + bb;
;                 sout[c * 65 + tt] = siluf(v);
;             }
;         }
	s_waitcnt vmcnt(0)
	v_mov_b32_e32 v0, v66
	v_mov_b32_e32 v1, v67
	v_mov_b32_e32 v2, v68
	s_cmp_gt_i32 s15, 31
	v_mov_b32_e32 v3, v69
	ds_read_b32 v6, v24
	ds_read2_b32 v[4:5], v25 offset0:65 offset1:130
	s_movk_i32 s50, 0xb00
	s_movk_i32 s51, 0x1600
	s_waitcnt vmcnt(2) lgkmcnt(0)
	v_mul_f32_e32 v4, v1, v4
	v_fmac_f32_e32 v4, v0, v6
	s_waitcnt vmcnt(1)
	v_fmac_f32_e32 v4, v2, v5
	s_waitcnt vmcnt(0)
	v_add_f32_e32 v4, v3, v4
	v_mul_f32_e32 v5, 0xbfb8aa3b, v4
	v_exp_f32_e32 v5, v5
	s_nop 0
	v_add_f32_e32 v5, 1.0, v5
	v_div_scale_f32 v6, s[18:19], v5, v5, v4
	v_rcp_f32_e32 v7, v6
	s_nop 0
	v_fma_f32 v14, -v6, v7, 1.0
	v_fmac_f32_e32 v7, v14, v7
	v_div_scale_f32 v14, vcc, v4, v5, v4
	v_mul_f32_e32 v15, v14, v7
	v_fma_f32 v43, -v6, v15, v14
	v_fmac_f32_e32 v15, v43, v7
	v_fma_f32 v6, -v6, v15, v14
	v_div_fmas_f32 v6, v6, v7, v15
	v_div_fixup_f32 v6, v6, v5, v4
	ds_read_b32 v7, v25 offset:1040
	ds_read2_b32 v[4:5], v27 offset0:65 offset1:130
	s_waitcnt lgkmcnt(0)
	v_mul_f32_e32 v4, v1, v4
	v_fmac_f32_e32 v4, v0, v7
	v_fmac_f32_e32 v4, v2, v5
	v_add_f32_e32 v4, v3, v4
	v_mul_f32_e32 v5, 0xbfb8aa3b, v4
	v_exp_f32_e32 v5, v5
	s_nop 0
	v_add_f32_e32 v5, 1.0, v5
	v_div_scale_f32 v7, s[18:19], v5, v5, v4
	v_rcp_f32_e32 v14, v7
	s_nop 0
	v_fma_f32 v15, -v7, v14, 1.0
	v_fmac_f32_e32 v14, v15, v14
	v_div_scale_f32 v15, vcc, v4, v5, v4
	v_mul_f32_e32 v43, v15, v14
	v_fma_f32 v44, -v7, v43, v15
	v_fmac_f32_e32 v43, v44, v14
	v_fma_f32 v7, -v7, v43, v15
	v_div_fmas_f32 v7, v7, v14, v43
	v_div_fixup_f32 v5, v7, v5, v4
	v_add_u32_e32 v4, 0x4000, v26
	ds_write2_b32 v4, v6, v5 offset0:194 offset1:198
	ds_read_b32 v5, v27 offset:1040
	ds_read2_b32 v[6:7], v28 offset0:65 offset1:130
	s_waitcnt lgkmcnt(0)
	v_mul_f32_e32 v6, v1, v6
	v_fmac_f32_e32 v6, v0, v5
	v_fmac_f32_e32 v6, v2, v7
	v_add_f32_e32 v5, v3, v6
	v_mul_f32_e32 v6, 0xbfb8aa3b, v5
	v_exp_f32_e32 v6, v6
	s_nop 0
	v_add_f32_e32 v6, 1.0, v6
	v_div_scale_f32 v7, s[18:19], v6, v6, v5
	v_rcp_f32_e32 v14, v7
	s_nop 0
	v_fma_f32 v15, -v7, v14, 1.0
	v_fmac_f32_e32 v14, v15, v14
	v_div_scale_f32 v15, vcc, v5, v6, v5
	v_mul_f32_e32 v43, v15, v14
	v_fma_f32 v44, -v7, v43, v15
	v_fmac_f32_e32 v43, v44, v14
	v_fma_f32 v7, -v7, v43, v15
	v_div_fmas_f32 v7, v7, v14, v43
	v_div_fixup_f32 v5, v7, v6, v5
	ds_read_b32 v14, v28 offset:1040
	ds_read2_b32 v[6:7], v29 offset0:65 offset1:130
	s_waitcnt lgkmcnt(0)
	v_mul_f32_e32 v6, v1, v6
	v_fmac_f32_e32 v6, v0, v14
	v_fmac_f32_e32 v6, v2, v7
	v_add_f32_e32 v6, v3, v6
	v_mul_f32_e32 v7, 0xbfb8aa3b, v6
	v_exp_f32_e32 v7, v7
	s_nop 0
	v_add_f32_e32 v7, 1.0, v7
	v_div_scale_f32 v14, s[18:19], v7, v7, v6
	v_rcp_f32_e32 v15, v14
	s_nop 0
	v_fma_f32 v43, -v14, v15, 1.0
	v_fmac_f32_e32 v15, v43, v15
	v_div_scale_f32 v43, vcc, v6, v7, v6
	v_mul_f32_e32 v44, v43, v15
	v_fma_f32 v45, -v14, v44, v43
	v_fmac_f32_e32 v44, v45, v15
	v_fma_f32 v14, -v14, v44, v43
	v_div_fmas_f32 v14, v14, v15, v44
	v_div_fixup_f32 v6, v14, v7, v6
	ds_write2_b32 v4, v5, v6 offset0:202 offset1:206
	ds_read_b32 v5, v29 offset:1040
	ds_read2_b32 v[6:7], v30 offset0:65 offset1:130
	s_waitcnt lgkmcnt(0)
	v_mul_f32_e32 v6, v1, v6
	v_fmac_f32_e32 v6, v0, v5
	v_fmac_f32_e32 v6, v2, v7
	v_add_f32_e32 v5, v3, v6
	v_mul_f32_e32 v6, 0xbfb8aa3b, v5
	v_exp_f32_e32 v6, v6
	s_nop 0
	v_add_f32_e32 v6, 1.0, v6
	v_div_scale_f32 v7, s[18:19], v6, v6, v5
	v_rcp_f32_e32 v14, v7
	s_nop 0
	v_fma_f32 v15, -v7, v14, 1.0
	v_fmac_f32_e32 v14, v15, v14
	v_div_scale_f32 v15, vcc, v5, v6, v5
	v_mul_f32_e32 v43, v15, v14
	v_fma_f32 v44, -v7, v43, v15
	v_fmac_f32_e32 v43, v44, v14
	v_fma_f32 v7, -v7, v43, v15
	v_div_fmas_f32 v7, v7, v14, v43
	v_div_fixup_f32 v5, v7, v6, v5
	ds_read_b32 v14, v30 offset:1040
	ds_read2_b32 v[6:7], v31 offset0:65 offset1:130
	s_waitcnt lgkmcnt(0)
	v_mul_f32_e32 v6, v1, v6
	v_fmac_f32_e32 v6, v0, v14
	v_fmac_f32_e32 v6, v2, v7
	v_add_f32_e32 v6, v3, v6
	v_mul_f32_e32 v7, 0xbfb8aa3b, v6
	v_exp_f32_e32 v7, v7
	s_nop 0
	v_add_f32_e32 v7, 1.0, v7
	v_div_scale_f32 v14, s[18:19], v7, v7, v6
	v_rcp_f32_e32 v15, v14
	s_nop 0
	v_fma_f32 v43, -v14, v15, 1.0
	v_fmac_f32_e32 v15, v43, v15
	v_div_scale_f32 v43, vcc, v6, v7, v6
	v_mul_f32_e32 v44, v43, v15
	v_fma_f32 v45, -v14, v44, v43
	v_fmac_f32_e32 v44, v45, v15
	v_fma_f32 v14, -v14, v44, v43
	v_div_fmas_f32 v14, v14, v15, v44
	v_div_fixup_f32 v6, v14, v7, v6
	ds_write2_b32 v4, v5, v6 offset0:210 offset1:214
	ds_read_b32 v5, v31 offset:1040
	ds_read2_b32 v[6:7], v32 offset0:65 offset1:130
	s_waitcnt lgkmcnt(0)
	v_mul_f32_e32 v6, v1, v6
	v_fmac_f32_e32 v6, v0, v5
	v_fmac_f32_e32 v6, v2, v7
	v_add_f32_e32 v5, v3, v6
	v_mul_f32_e32 v6, 0xbfb8aa3b, v5
	v_exp_f32_e32 v6, v6
	s_nop 0
	v_add_f32_e32 v6, 1.0, v6
	v_div_scale_f32 v7, s[18:19], v6, v6, v5
	v_rcp_f32_e32 v14, v7
	s_nop 0
	v_fma_f32 v15, -v7, v14, 1.0
	v_fmac_f32_e32 v14, v15, v14
	v_div_scale_f32 v15, vcc, v5, v6, v5
	v_mul_f32_e32 v43, v15, v14
	v_fma_f32 v44, -v7, v43, v15
	v_fmac_f32_e32 v43, v44, v14
	v_fma_f32 v7, -v7, v43, v15
	v_div_fmas_f32 v7, v7, v14, v43
	v_div_fixup_f32 v5, v7, v6, v5
	ds_read_b32 v14, v32 offset:1040
	ds_read2_b32 v[6:7], v33 offset0:65 offset1:130
	s_waitcnt lgkmcnt(0)
	v_mul_f32_e32 v6, v1, v6
	v_fmac_f32_e32 v6, v0, v14
	v_fmac_f32_e32 v6, v2, v7
	v_add_f32_e32 v6, v3, v6
	v_mul_f32_e32 v7, 0xbfb8aa3b, v6
	v_exp_f32_e32 v7, v7
	s_nop 0
	v_add_f32_e32 v7, 1.0, v7
	v_div_scale_f32 v14, s[18:19], v7, v7, v6
	v_rcp_f32_e32 v15, v14
	s_nop 0
	v_fma_f32 v43, -v14, v15, 1.0
	v_fmac_f32_e32 v15, v43, v15
	v_div_scale_f32 v43, vcc, v6, v7, v6
	v_mul_f32_e32 v44, v43, v15
	v_fma_f32 v45, -v14, v44, v43
	v_fmac_f32_e32 v44, v45, v15
	v_fma_f32 v14, -v14, v44, v43
	v_div_fmas_f32 v14, v14, v15, v44
	v_div_fixup_f32 v6, v14, v7, v6
	ds_write2_b32 v4, v5, v6 offset0:218 offset1:222
	ds_read_b32 v6, v33 offset:1040
	ds_read2_b32 v[4:5], v34 offset0:65 offset1:130
	s_waitcnt lgkmcnt(0)
; __device__ __forceinline__ unsigned pack2(float a, float b) { const f32v2_t v = {a, b}; return __builtin_bit_cast(unsigned, __builtin_convertvector(v, bf16v2_t)); }
; __device__ __forceinline__ float siluf(float v) { return v / (1.f + __expf(-v)); }
; __device__ __forceinline__ void conv_phase(CParams& p, int layer, float* smf) {
;     ...
;             const int c = tid & 63;
;             const float w0 = cw[c0 + c], w1 = cw[3072 + c0 + c], w2 = cw[2 * 3072 + c0 + c], bb = cb[c0 + c];
; #pragma unroll
;             for (int k = 0; k < 16; ++k) {
;                 const int tt = (tid >> 6) + k * 4;
;                 const float v = w0 * sin_[tt * 65 + c] + w1 * sin_[(tt + 1) * 65 + c] + w2 * sin_[(tt + 2) * 65 + c] + bb;
;                 sout[c * 65 + tt] = siluf(v);
;             }
;         }
;         lds_sync();
;         const int q = tid >> 2, e16 = (tid & 3) * 16;
;         if (c0 >= 2048) {
;             u32x4 o0, o1;
;             o0.x = pack2(sout[(e16 + 0) * 65 + q], sout[(e16 + 1) * 65 + q]); o0.y = pack2(sout[(e16 + 2) * 65 + q], sout[(e16 + 3) * 65 + q]);
;             o0.z = pack2(sout[(e16 + 4) * 65 + q], sout[(e16 + 5) * 65 + q]); o0.w = pack2(sout[(e16 + 6) * 65 + q], sout[(e16 + 7) * 65 + q]);
;             o1.x = pack2(sout[(e16 + 8) * 65 + q], sout[(e16 + 9) * 65 + q]); o1.y = pack2(sout[(e16 + 10) * 65 + q], sout[(e16 + 11) * 65 + q]);
;             o1.z = pack2(sout[(e16 + 12) * 65 + q], sout[(e16 + 13) * 65 + q]); o1.w = pack2(sout[(e16 + 14) * 65 + q], sout[(e16 + 15) * 65 + q]);
;             if (c0 < 2560) {
;                 bf16_t* dst = Bn + (c0 - 2048) + (size_t)(r0 + q) * 512 + e16;
;                 *(u32x4*)dst = o0; *(u32x4*)(dst + 8) = o1;
;             } else {
;                 *(u32x4*)(Cn + frag_off(r0 + q, c0 - 2560 + e16, 512)) = o0;
;                 *(u32x4*)(Cn + frag_off(r0 + q, c0 - 2560 + e16 + 8, 512)) = o1;
	v_mul_f32_e32 v4, v1, v4
	v_fmac_f32_e32 v4, v0, v6
	v_fmac_f32_e32 v4, v2, v5
	v_add_f32_e32 v4, v3, v4
	v_mul_f32_e32 v5, 0xbfb8aa3b, v4
	v_exp_f32_e32 v5, v5
	s_nop 0
	v_add_f32_e32 v5, 1.0, v5
	v_div_scale_f32 v6, s[18:19], v5, v5, v4
	v_rcp_f32_e32 v7, v6
	s_nop 0
	v_fma_f32 v14, -v6, v7, 1.0
	v_fmac_f32_e32 v7, v14, v7
	v_div_scale_f32 v14, vcc, v4, v5, v4
	v_mul_f32_e32 v15, v14, v7
	v_fma_f32 v43, -v6, v15, v14
	v_fmac_f32_e32 v15, v43, v7
	v_fma_f32 v6, -v6, v15, v14
	v_div_fmas_f32 v6, v6, v7, v15
	v_div_fixup_f32 v4, v6, v5, v4
	ds_write_b32 v26, v4 offset:17288
	ds_read_b32 v6, v34 offset:1040
	ds_read2_b32 v[4:5], v35 offset0:65 offset1:130
	s_waitcnt lgkmcnt(0)
	v_mul_f32_e32 v4, v1, v4
	v_fmac_f32_e32 v4, v0, v6
	v_fmac_f32_e32 v4, v2, v5
	v_add_f32_e32 v4, v3, v4
	v_mul_f32_e32 v5, 0xbfb8aa3b, v4
	v_exp_f32_e32 v5, v5
	s_nop 0
	v_add_f32_e32 v5, 1.0, v5
	v_div_scale_f32 v6, s[18:19], v5, v5, v4
	v_rcp_f32_e32 v7, v6
	s_nop 0
	v_fma_f32 v14, -v6, v7, 1.0
	v_fmac_f32_e32 v7, v14, v7
	v_div_scale_f32 v14, vcc, v4, v5, v4
	v_mul_f32_e32 v15, v14, v7
	v_fma_f32 v43, -v6, v15, v14
	v_fmac_f32_e32 v15, v43, v7
	v_fma_f32 v6, -v6, v15, v14
	v_div_fmas_f32 v6, v6, v7, v15
	v_div_fixup_f32 v4, v6, v5, v4
	ds_write_b32 v26, v4 offset:17304
	ds_read_b32 v6, v35 offset:1040
	ds_read2_b32 v[4:5], v36 offset0:65 offset1:130
	s_waitcnt lgkmcnt(0)
	v_mul_f32_e32 v4, v1, v4
	v_fmac_f32_e32 v4, v0, v6
	v_fmac_f32_e32 v4, v2, v5
	v_add_f32_e32 v4, v3, v4
	v_mul_f32_e32 v5, 0xbfb8aa3b, v4
	v_exp_f32_e32 v5, v5
	s_nop 0
	v_add_f32_e32 v5, 1.0, v5
	v_div_scale_f32 v6, s[18:19], v5, v5, v4
	v_rcp_f32_e32 v7, v6
	s_nop 0
	v_fma_f32 v14, -v6, v7, 1.0
	v_fmac_f32_e32 v7, v14, v7
	v_div_scale_f32 v14, vcc, v4, v5, v4
	v_mul_f32_e32 v15, v14, v7
	v_fma_f32 v43, -v6, v15, v14
	v_fmac_f32_e32 v15, v43, v7
	v_fma_f32 v6, -v6, v15, v14
	v_div_fmas_f32 v6, v6, v7, v15
	v_div_fixup_f32 v4, v6, v5, v4
	ds_write_b32 v26, v4 offset:17320
	ds_read_b32 v6, v36 offset:1040
	ds_read2_b32 v[4:5], v37 offset0:65 offset1:130
	s_waitcnt lgkmcnt(0)
	v_mul_f32_e32 v4, v1, v4
	v_fmac_f32_e32 v4, v0, v6
	v_fmac_f32_e32 v4, v2, v5
	v_add_f32_e32 v4, v3, v4
	v_mul_f32_e32 v5, 0xbfb8aa3b, v4
	v_exp_f32_e32 v5, v5
	s_nop 0
	v_add_f32_e32 v5, 1.0, v5
	v_div_scale_f32 v6, s[18:19], v5, v5, v4
	v_rcp_f32_e32 v7, v6
	s_nop 0
	v_fma_f32 v14, -v6, v7, 1.0
	v_fmac_f32_e32 v7, v14, v7
	v_div_scale_f32 v14, vcc, v4, v5, v4
	v_mul_f32_e32 v15, v14, v7
	v_fma_f32 v43, -v6, v15, v14
	v_fmac_f32_e32 v15, v43, v7
	v_fma_f32 v6, -v6, v15, v14
	v_div_fmas_f32 v6, v6, v7, v15
	v_div_fixup_f32 v4, v6, v5, v4
	ds_write_b32 v26, v4 offset:17336
	ds_read_b32 v6, v37 offset:1040
	ds_read2_b32 v[4:5], v38 offset0:65 offset1:130
	s_waitcnt lgkmcnt(0)
	v_mul_f32_e32 v4, v1, v4
	v_fmac_f32_e32 v4, v0, v6
	v_fmac_f32_e32 v4, v2, v5
	v_add_f32_e32 v4, v3, v4
	v_mul_f32_e32 v5, 0xbfb8aa3b, v4
	v_exp_f32_e32 v5, v5
	s_nop 0
	v_add_f32_e32 v5, 1.0, v5
	v_div_scale_f32 v6, s[18:19], v5, v5, v4
	v_rcp_f32_e32 v7, v6
	s_nop 0
	v_fma_f32 v14, -v6, v7, 1.0
	v_fmac_f32_e32 v7, v14, v7
	v_div_scale_f32 v14, vcc, v4, v5, v4
	v_mul_f32_e32 v15, v14, v7
	v_fma_f32 v43, -v6, v15, v14
	v_fmac_f32_e32 v15, v43, v7
	v_fma_f32 v6, -v6, v15, v14
	v_div_fmas_f32 v6, v6, v7, v15
	v_div_fixup_f32 v4, v6, v5, v4
	ds_write_b32 v26, v4 offset:17352
	ds_read_b32 v6, v38 offset:1040
	ds_read2_b32 v[4:5], v39 offset0:65 offset1:130
	s_waitcnt lgkmcnt(0)
	v_mul_f32_e32 v4, v1, v4
	v_fmac_f32_e32 v4, v0, v6
	v_fmac_f32_e32 v4, v2, v5
	v_add_f32_e32 v4, v3, v4
	v_mul_f32_e32 v5, 0xbfb8aa3b, v4
	v_exp_f32_e32 v5, v5
	s_nop 0
	v_add_f32_e32 v5, 1.0, v5
	v_div_scale_f32 v6, s[18:19], v5, v5, v4
	v_rcp_f32_e32 v7, v6
	s_nop 0
	v_fma_f32 v14, -v6, v7, 1.0
	v_fmac_f32_e32 v7, v14, v7
	v_div_scale_f32 v14, vcc, v4, v5, v4
	v_mul_f32_e32 v15, v14, v7
	v_fma_f32 v43, -v6, v15, v14
	v_fmac_f32_e32 v15, v43, v7
	v_fma_f32 v6, -v6, v15, v14
	v_div_fmas_f32 v6, v6, v7, v15
	v_div_fixup_f32 v4, v6, v5, v4
	ds_write_b32 v26, v4 offset:17368
	ds_read_b32 v6, v39 offset:1040
	ds_read2_b32 v[4:5], v40 offset0:65 offset1:130
	s_waitcnt lgkmcnt(0)
	v_mul_f32_e32 v4, v1, v4
	v_fmac_f32_e32 v4, v0, v6
	v_fmac_f32_e32 v4, v2, v5
	v_add_f32_e32 v4, v3, v4
	v_mul_f32_e32 v5, 0xbfb8aa3b, v4
	v_exp_f32_e32 v5, v5
	s_nop 0
	v_add_f32_e32 v5, 1.0, v5
	v_div_scale_f32 v6, s[18:19], v5, v5, v4
	v_rcp_f32_e32 v7, v6
	s_nop 0
	v_fma_f32 v14, -v6, v7, 1.0
	v_fmac_f32_e32 v7, v14, v7
	v_div_scale_f32 v14, vcc, v4, v5, v4
	v_mul_f32_e32 v15, v14, v7
	v_fma_f32 v43, -v6, v15, v14
	v_fmac_f32_e32 v15, v43, v7
	v_fma_f32 v6, -v6, v15, v14
	v_div_fmas_f32 v6, v6, v7, v15
	v_div_fixup_f32 v4, v6, v5, v4
	ds_write_b32 v26, v4 offset:17384
	ds_read_b32 v6, v40 offset:1040
	ds_read2_b32 v[4:5], v41 offset0:65 offset1:130
	s_waitcnt lgkmcnt(0)
	v_mul_f32_e32 v1, v1, v4
	v_fmac_f32_e32 v1, v0, v6
	v_fmac_f32_e32 v1, v2, v5
	v_add_f32_e32 v0, v3, v1
	v_mul_f32_e32 v1, 0xbfb8aa3b, v0
	v_exp_f32_e32 v1, v1
	s_nop 0
	v_add_f32_e32 v1, 1.0, v1
	v_div_scale_f32 v2, s[18:19], v1, v1, v0
	v_rcp_f32_e32 v3, v2
	s_nop 0
	v_fma_f32 v4, -v2, v3, 1.0
	v_fmac_f32_e32 v3, v4, v3
	v_div_scale_f32 v4, vcc, v0, v1, v0
	v_mul_f32_e32 v5, v4, v3
	v_fma_f32 v6, -v2, v5, v4
	v_fmac_f32_e32 v5, v6, v3
	v_fma_f32 v2, -v2, v5, v4
	v_div_fmas_f32 v2, v2, v3, v5
	v_div_fixup_f32 v0, v2, v1, v0
	ds_write_b32 v26, v0 offset:17400
	s_waitcnt lgkmcnt(0)
	s_barrier
	s_cbranch_scc0 .LBB0_416
	v_add_u32_e32 v0, 0x4200, v20
	ds_read2_b32 v[0:1], v0 offset0:66 offset1:131
	s_mov_b64 s[18:19], -1
	s_cmp_gt_u32 s15, 39
	s_waitcnt lgkmcnt(0)
	v_cvt_pk_bf16_f32 v0, v0, v1
	v_add_u32_e32 v1, 0x4400, v20
	ds_read2_b32 v[2:3], v1 offset0:68 offset1:133
	s_waitcnt lgkmcnt(0)
	v_cvt_pk_bf16_f32 v1, v2, v3
	v_add_u32_e32 v2, 0x4600, v20
	ds_read2_b32 v[2:3], v2 offset0:70 offset1:135
	s_waitcnt lgkmcnt(0)
	v_cvt_pk_bf16_f32 v2, v2, v3
	v_add_u32_e32 v3, 0x4800, v20
	ds_read2_b32 v[4:5], v3 offset0:72 offset1:137
	s_waitcnt lgkmcnt(0)
	v_cvt_pk_bf16_f32 v3, v4, v5
	v_add_u32_e32 v4, 0x4a00, v20
	ds_read2_b32 v[4:5], v4 offset0:74 offset1:139
	s_waitcnt lgkmcnt(0)
	v_cvt_pk_bf16_f32 v4, v4, v5
	v_add_u32_e32 v5, 0x4c00, v20
	ds_read2_b32 v[6:7], v5 offset0:76 offset1:141
	s_waitcnt lgkmcnt(0)
	v_cvt_pk_bf16_f32 v5, v6, v7
	v_add_u32_e32 v6, 0x4e00, v20
	ds_read2_b32 v[6:7], v6 offset0:78 offset1:143
	s_waitcnt lgkmcnt(0)
	v_cvt_pk_bf16_f32 v6, v6, v7
	v_add_u32_e32 v7, 0x5000, v20
	ds_read2_b32 v[14:15], v7 offset0:80 offset1:145
	s_waitcnt lgkmcnt(0)
	v_cvt_pk_bf16_f32 v7, v14, v15
	v_add_u32_e32 v14, s14, v19
	s_cbranch_scc0 .LBB0_414
	v_add_u32_e32 v15, s16, v21
	v_ashrrev_i32_e32 v44, 4, v14
	v_ashrrev_i32_e32 v45, 31, v44
	v_ashrrev_i32_e32 v46, 5, v15
	v_ashrrev_i32_e32 v47, 31, v46
	v_lshlrev_b64 v[44:45], 14, v[44:45]
	v_lshlrev_b64 v[46:47], 10, v[46:47]
	v_lshl_add_u64 v[44:45], v[10:11], 0, v[44:45]
	v_lshl_add_u64 v[44:45], v[44:45], 0, v[46:47]
	global_store_dwordx4 v[44:45], v[0:3], off
	global_store_dwordx4 v[44:45], v[4:7], off offset:256
	s_mov_b64 s[18:19], 0
